# NA bias-table build: the 10 global loads issued back to back behind one wait instead of 10 serialized round trips
# baseline (speedup 1.0000x reference)
.LBB0_1698:
	s_cmpk_lt_i32 s2, 0x200
	v_writelane_b32 v250, s86, 1
	s_cselect_b64 s[0:1], -1, 0
	v_writelane_b32 v250, s0, 2
	s_cmpk_gt_i32 s2, 0x1ff
	v_and_b32_e32 v160, 31, v0
	v_lshrrev_b32_e32 v1, 5, v198
	v_lshlrev_b32_e32 v178, 4, v0
	v_lshrrev_b32_e32 v147, 3, v0
	v_writelane_b32 v250, s1, 3
	v_writelane_b32 v251, s2, 61
	s_cbranch_scc1 .LBB0_1875
	v_readlane_b32 s4, v251, 48
	v_readlane_b32 s5, v251, 49
	v_readlane_b32 s6, v251, 15
	v_readlane_b32 s7, v251, 16
	v_readlane_b32 s8, v251, 52
	v_readlane_b32 s9, v251, 23
	v_readlane_b32 s10, v251, 61
	s_nop 3
	s_and_b32 s11, s8, 1
	v_and_b32_e32 v216, 31, v0
	v_bfe_u32 v217, v0, 5, 1
	v_mov_b32_e32 v228, 0
	v_mov_b32_e32 v229, 0xf149f2ca
	s_lshl_b32 s36, s11, 5
	v_add_u32_e32 v222, s36, v216
	v_mul_u32_u24_e32 v199, 0x90, v222
	v_lshl_add_u32 v199, v217, 4, v199
	s_cmp_eq_u32 s11, 0
	s_cselect_b32 s37, 0, 24
	s_cselect_b32 s38, 32, 0
	v_add_u32_e32 v222, s37, v216
	v_and_b32_e32 v222, 31, v222
	v_add_u32_e32 v222, s38, v222
	v_mul_u32_u24_e32 v200, 0x90, v222
	v_lshl_add_u32 v200, v217, 4, v200
	v_mul_u32_u24_e32 v222, 0x88, v216
	v_lshl_add_u32 v222, v217, 3, v222
	v_add_u32_e32 v222, 0x4800, v222
	s_lshl_b32 s36, s11, 6
	v_add_u32_e32 v201, s36, v222
	s_cmp_eq_u32 s11, 0
	s_cselect_b32 s37, 64, 48
	s_cselect_b32 s38, 0x50, 0
	v_add_u32_e32 v202, s37, v222
	v_add_u32_e32 v203, s38, v222
	v_lshrrev_b32_e32 v222, 3, v0
	v_and_b32_e32 v223, 7, v0
	v_mul_u32_u24_e32 v204, 0x90, v222
	v_lshl_add_u32 v204, v223, 4, v204
	v_mul_u32_u24_e32 v205, 0x88, v222
	v_lshl_add_u32 v205, v223, 4, v205
	v_add_u32_e32 v205, 0x4800, v205
	v_lshlrev_b32_e32 v206, 4, v0
	v_mul_u32_u24_e32 v207, 0x2200, v222
	v_lshl_add_u32 v207, v223, 4, v207
	v_lshl_or_b32 v222, s8, 5, v216
	v_lshlrev_b32_e32 v219, 7, v222
	v_lshl_add_u32 v219, v217, 4, v219
	v_lshlrev_b32_e32 v218, 10, v222
	v_lshl_add_u32 v218, v217, 3, v218
	v_and_b32_e32 v222, 3, v216
	v_add_u32_e32 v223, 1, v222
	v_and_b32_e32 v223, 3, v223
	v_lshl_add_u32 v223, v217, 2, v223
	v_sub_u32_e32 v223, v223, v216
	v_add_u32_e32 v223, 39, v223
	v_lshlrev_b32_e32 v223, 2, v223
	v_mul_u32_u24_e32 v222, 5040, v222
	v_add_u32_e32 v208, v222, v223
	v_add_u32_e32 v208, 0x8c00, v208
	s_cmp_eq_u32 s11, 0
	s_mov_b32 s37, 0x80
	s_cselect_b32 s37, s37, 0xffffffe0
	v_add_u32_e32 v209, s37, v208
	v_mov_b32_e32 v186, 0
	v_mov_b32_e32 v187, 0
	s_lshr_b32 s36, s10, 4
	s_and_b32 s36, s36, 7
	s_mul_i32 s36, s36, 0x744
	s_add_u32 s38, s6, s36
	s_addc_u32 s39, s7, 0
	s_mov_b32 s36, 0xd00e
	v_mov_b32_e32 v222, v0
	v_mul_lo_u32 v223, v222, s36
	v_lshrrev_b32_e32 v223, 26, v223
	v_mul_u32_u24_e32 v224, 1260, v223
	v_sub_u32_e32 v224, v222, v224
	v_mul_u32_u24_e32 v225, 49933, v224
	v_lshrrev_b32_e32 v225, 22, v225
	v_mul_u32_u24_e32 v226, 84, v225
	v_sub_u32_e32 v226, v224, v226
	v_add_u32_e32 v227, 1, v223
	v_and_b32_e32 v227, 3, v227
	v_sub_u32_e32 v226, v226, v227
	v_subrev_u32_e32 v226, 24, v226
	v_cmp_gt_u32_e64 s[40:41], 31, v226
	s_nop 1
	v_cndmask_b32_e64 v227, 0, v226, s[40:41]
	v_mad_u32_u24 v227, v225, 31, v227
	v_lshlrev_b32_e32 v227, 2, v227
	global_load_dword v34, v227, s[38:39]
	v_add_u32_e32 v222, 512, v0
	v_mul_lo_u32 v223, v222, s36
	v_lshrrev_b32_e32 v223, 26, v223
	v_mul_u32_u24_e32 v224, 1260, v223
	v_sub_u32_e32 v224, v222, v224
	v_mul_u32_u24_e32 v225, 49933, v224
	v_lshrrev_b32_e32 v225, 22, v225
	v_mul_u32_u24_e32 v226, 84, v225
	v_sub_u32_e32 v226, v224, v226
	v_add_u32_e32 v227, 1, v223
	v_and_b32_e32 v227, 3, v227
	v_sub_u32_e32 v226, v226, v227
	v_subrev_u32_e32 v226, 24, v226
	v_cmp_gt_u32_e64 s[42:43], 31, v226
	s_nop 1
	v_cndmask_b32_e64 v227, 0, v226, s[42:43]
	v_mad_u32_u24 v227, v225, 31, v227
	v_lshlrev_b32_e32 v227, 2, v227
	global_load_dword v35, v227, s[38:39]
	v_add_u32_e32 v222, 1024, v0
	v_mul_lo_u32 v223, v222, s36
	v_lshrrev_b32_e32 v223, 26, v223
	v_mul_u32_u24_e32 v224, 1260, v223
	v_sub_u32_e32 v224, v222, v224
	v_mul_u32_u24_e32 v225, 49933, v224
	v_lshrrev_b32_e32 v225, 22, v225
	v_mul_u32_u24_e32 v226, 84, v225
	v_sub_u32_e32 v226, v224, v226
	v_add_u32_e32 v227, 1, v223
	v_and_b32_e32 v227, 3, v227
	v_sub_u32_e32 v226, v226, v227
	v_subrev_u32_e32 v226, 24, v226
	v_cmp_gt_u32_e64 s[44:45], 31, v226
	s_nop 1
	v_cndmask_b32_e64 v227, 0, v226, s[44:45]
	v_mad_u32_u24 v227, v225, 31, v227
	v_lshlrev_b32_e32 v227, 2, v227
	global_load_dword v36, v227, s[38:39]
	v_add_u32_e32 v222, 1536, v0
	v_mul_lo_u32 v223, v222, s36
	v_lshrrev_b32_e32 v223, 26, v223
	v_mul_u32_u24_e32 v224, 1260, v223
	v_sub_u32_e32 v224, v222, v224
	v_mul_u32_u24_e32 v225, 49933, v224
	v_lshrrev_b32_e32 v225, 22, v225
	v_mul_u32_u24_e32 v226, 84, v225
	v_sub_u32_e32 v226, v224, v226
	v_add_u32_e32 v227, 1, v223
	v_and_b32_e32 v227, 3, v227
	v_sub_u32_e32 v226, v226, v227
	v_subrev_u32_e32 v226, 24, v226
	v_cmp_gt_u32_e64 s[46:47], 31, v226
	s_nop 1
	v_cndmask_b32_e64 v227, 0, v226, s[46:47]
	v_mad_u32_u24 v227, v225, 31, v227
	v_lshlrev_b32_e32 v227, 2, v227
	global_load_dword v37, v227, s[38:39]
	v_add_u32_e32 v222, 2048, v0
	v_mul_lo_u32 v223, v222, s36
	v_lshrrev_b32_e32 v223, 26, v223
	v_mul_u32_u24_e32 v224, 1260, v223
	v_sub_u32_e32 v224, v222, v224
	v_mul_u32_u24_e32 v225, 49933, v224
	v_lshrrev_b32_e32 v225, 22, v225
	v_mul_u32_u24_e32 v226, 84, v225
	v_sub_u32_e32 v226, v224, v226
	v_add_u32_e32 v227, 1, v223
	v_and_b32_e32 v227, 3, v227
	v_sub_u32_e32 v226, v226, v227
	v_subrev_u32_e32 v226, 24, v226
	v_cmp_gt_u32_e64 s[48:49], 31, v226
	s_nop 1
	v_cndmask_b32_e64 v227, 0, v226, s[48:49]
	v_mad_u32_u24 v227, v225, 31, v227
	v_lshlrev_b32_e32 v227, 2, v227
	global_load_dword v38, v227, s[38:39]
	v_add_u32_e32 v222, 2560, v0
	v_mul_lo_u32 v223, v222, s36
	v_lshrrev_b32_e32 v223, 26, v223
	v_mul_u32_u24_e32 v224, 1260, v223
	v_sub_u32_e32 v224, v222, v224
	v_mul_u32_u24_e32 v225, 49933, v224
	v_lshrrev_b32_e32 v225, 22, v225
	v_mul_u32_u24_e32 v226, 84, v225
	v_sub_u32_e32 v226, v224, v226
	v_add_u32_e32 v227, 1, v223
	v_and_b32_e32 v227, 3, v227
	v_sub_u32_e32 v226, v226, v227
	v_subrev_u32_e32 v226, 24, v226
	v_cmp_gt_u32_e64 s[50:51], 31, v226
	s_nop 1
	v_cndmask_b32_e64 v227, 0, v226, s[50:51]
	v_mad_u32_u24 v227, v225, 31, v227
	v_lshlrev_b32_e32 v227, 2, v227
	global_load_dword v39, v227, s[38:39]
	v_add_u32_e32 v222, 3072, v0
	v_mul_lo_u32 v223, v222, s36
	v_lshrrev_b32_e32 v223, 26, v223
	v_mul_u32_u24_e32 v224, 1260, v223
	v_sub_u32_e32 v224, v222, v224
	v_mul_u32_u24_e32 v225, 49933, v224
	v_lshrrev_b32_e32 v225, 22, v225
	v_mul_u32_u24_e32 v226, 84, v225
	v_sub_u32_e32 v226, v224, v226
	v_add_u32_e32 v227, 1, v223
	v_and_b32_e32 v227, 3, v227
	v_sub_u32_e32 v226, v226, v227
	v_subrev_u32_e32 v226, 24, v226
	v_cmp_gt_u32_e64 s[52:53], 31, v226
	s_nop 1
	v_cndmask_b32_e64 v227, 0, v226, s[52:53]
	v_mad_u32_u24 v227, v225, 31, v227
	v_lshlrev_b32_e32 v227, 2, v227
	global_load_dword v40, v227, s[38:39]
	v_add_u32_e32 v222, 3584, v0
	v_mul_lo_u32 v223, v222, s36
	v_lshrrev_b32_e32 v223, 26, v223
	v_mul_u32_u24_e32 v224, 1260, v223
	v_sub_u32_e32 v224, v222, v224
	v_mul_u32_u24_e32 v225, 49933, v224
	v_lshrrev_b32_e32 v225, 22, v225
	v_mul_u32_u24_e32 v226, 84, v225
	v_sub_u32_e32 v226, v224, v226
	v_add_u32_e32 v227, 1, v223
	v_and_b32_e32 v227, 3, v227
	v_sub_u32_e32 v226, v226, v227
	v_subrev_u32_e32 v226, 24, v226
	v_cmp_gt_u32_e64 s[54:55], 31, v226
	s_nop 1
	v_cndmask_b32_e64 v227, 0, v226, s[54:55]
	v_mad_u32_u24 v227, v225, 31, v227
	v_lshlrev_b32_e32 v227, 2, v227
	global_load_dword v41, v227, s[38:39]
	v_add_u32_e32 v222, 4096, v0
	v_mul_lo_u32 v223, v222, s36
	v_lshrrev_b32_e32 v223, 26, v223
	v_mul_u32_u24_e32 v224, 1260, v223
	v_sub_u32_e32 v224, v222, v224
	v_mul_u32_u24_e32 v225, 49933, v224
	v_lshrrev_b32_e32 v225, 22, v225
	v_mul_u32_u24_e32 v226, 84, v225
	v_sub_u32_e32 v226, v224, v226
	v_add_u32_e32 v227, 1, v223
	v_and_b32_e32 v227, 3, v227
	v_sub_u32_e32 v226, v226, v227
	v_subrev_u32_e32 v226, 24, v226
	v_cmp_gt_u32_e64 s[56:57], 31, v226
	s_nop 1
	v_cndmask_b32_e64 v227, 0, v226, s[56:57]
	v_mad_u32_u24 v227, v225, 31, v227
	v_lshlrev_b32_e32 v227, 2, v227
	global_load_dword v42, v227, s[38:39]
	v_add_u32_e32 v222, 4608, v0
	v_mul_lo_u32 v223, v222, s36
	v_lshrrev_b32_e32 v223, 26, v223
	v_mul_u32_u24_e32 v224, 1260, v223
	v_sub_u32_e32 v224, v222, v224
	v_mul_u32_u24_e32 v225, 49933, v224
	v_lshrrev_b32_e32 v225, 22, v225
	v_mul_u32_u24_e32 v226, 84, v225
	v_sub_u32_e32 v226, v224, v226
	v_add_u32_e32 v227, 1, v223
	v_and_b32_e32 v227, 3, v227
	v_sub_u32_e32 v226, v226, v227
	v_subrev_u32_e32 v226, 24, v226
	v_cmp_gt_u32_e64 s[58:59], 31, v226
	s_nop 1
	v_cndmask_b32_e64 v227, 0, v226, s[58:59]
	v_mad_u32_u24 v227, v225, 31, v227
	v_lshlrev_b32_e32 v227, 2, v227
	global_load_dword v43, v227, s[38:39]
	v_lshlrev_b32_e32 v222, 2, v0
	s_waitcnt vmcnt(0)
	v_mul_f32_e32 v34, 0x3fb8aa3b, v34
	v_cndmask_b32_e64 v34, 0, v34, s[40:41]
	v_mul_f32_e32 v35, 0x3fb8aa3b, v35
	v_cndmask_b32_e64 v35, 0, v35, s[42:43]
	v_mul_f32_e32 v36, 0x3fb8aa3b, v36
	v_cndmask_b32_e64 v36, 0, v36, s[44:45]
	v_mul_f32_e32 v37, 0x3fb8aa3b, v37
	v_cndmask_b32_e64 v37, 0, v37, s[46:47]
	v_mul_f32_e32 v38, 0x3fb8aa3b, v38
	v_cndmask_b32_e64 v38, 0, v38, s[48:49]
	v_mul_f32_e32 v39, 0x3fb8aa3b, v39
	v_cndmask_b32_e64 v39, 0, v39, s[50:51]
	v_mul_f32_e32 v40, 0x3fb8aa3b, v40
	v_cndmask_b32_e64 v40, 0, v40, s[52:53]
	v_mul_f32_e32 v41, 0x3fb8aa3b, v41
	v_cndmask_b32_e64 v41, 0, v41, s[54:55]
	v_mul_f32_e32 v42, 0x3fb8aa3b, v42
	v_cndmask_b32_e64 v42, 0, v42, s[56:57]
	v_mul_f32_e32 v43, 0x3fb8aa3b, v43
	v_cndmask_b32_e64 v43, 0, v43, s[58:59]
	v_cmp_gt_u32_e32 vcc, 432, v0
	ds_write_b32 v222, v34 offset:35840
	ds_write_b32 v222, v35 offset:37888
	ds_write_b32 v222, v36 offset:39936
	ds_write_b32 v222, v37 offset:41984
	ds_write_b32 v222, v38 offset:44032
	ds_write_b32 v222, v39 offset:46080
	ds_write_b32 v222, v40 offset:48128
	ds_write_b32 v222, v41 offset:50176
	ds_write_b32 v222, v42 offset:52224
	s_and_saveexec_b64 s[60:61], vcc
	ds_write_b32 v222, v43 offset:54272
	s_mov_b64 exec, s[60:61]
